# lse record written write-through (sc0 sc1) so no cross-XCD false-shared dirty line exists when the barrier acquire runs at arrival
# baseline (speedup 1.0000x reference)
; __device__ __forceinline__ void phase_dilated_mfma(const PT a, unsigned char* ldsb, int tid, int lane, int wave, int bid, int nblk) {
;     ...
;         if (act) {
;             const float lt = l + __shfl_xor(l, 32), inv = 1.0f / lt;
;             float* op = oag + ((size_t)g * M + tok) * 512 + h * 64;
; #pragma unroll
;             for (int ds = 0; ds < 2; ++ds)
; #pragma unroll
;                 for (int i4 = 0; i4 < 4; ++i4) { f32x4 v; v.x = O[ds][i4 * 4 + 0] * inv; v.y = O[ds][i4 * 4 + 1] * inv; v.z = O[ds][i4 * 4 + 2] * inv; v.w = O[ds][i4 * 4 + 3] * inv;
;                     *(f32x4*)(op + ds * 32 + i4 * 8 + 4 * hi) = v; }
;             if (hi == 0) lseb[((size_t)g * M + tok) * 8 + h] = (m + __log2f(lt)) * 0.6931471805599453f;
;         }
.LBB0_338:
	v_ashrrev_i32_e32 v107, 31, v106
	s_andn2_b64 vcc, exec, s[16:17]
	s_cbranch_vccnz .LBB0_303
	v_and_b32_e32 v34, 64, v220
	v_xor_b32_e32 v0, 32, v220
	v_add_u32_e32 v34, 64, v34
	v_cmp_lt_i32_e32 vcc, v0, v34
	s_lshl_b32 s90, s34, 13
	s_nop 0
	v_cndmask_b32_e32 v0, v220, v0, vcc
	v_lshlrev_b32_e32 v0, 2, v0
	ds_bpermute_b32 v0, v0, v120
	s_waitcnt lgkmcnt(0)
	v_add_f32_e32 v36, v120, v0
	v_div_scale_f32 v0, s[0:1], v36, v36, 1.0
	v_rcp_f32_e32 v34, v0
	v_div_scale_f32 v35, vcc, 1.0, v36, 1.0
	v_fma_f32 v37, -v0, v34, 1.0
	v_fmac_f32_e32 v34, v37, v34
	v_mul_f32_e32 v37, v35, v34
	v_fma_f32 v38, -v0, v37, v35
	v_fmac_f32_e32 v37, v38, v34
	v_fma_f32 v0, -v0, v37, v35
	v_div_fmas_f32 v0, v0, v34, v37
	v_lshl_add_u64 v[34:35], v[106:107], 0, s[90:91]
	v_lshlrev_b64 v[40:41], 11, v[34:35]
	v_lshl_add_u64 v[40:41], s[12:13], 0, v[40:41]
	s_lshl_b32 s90, s36, 2
	v_div_fixup_f32 v38, v0, v36, 1.0
	v_lshl_add_u64 v[40:41], v[40:41], 0, s[90:91]
	v_lshlrev_b32_e32 v0, 2, v102
	v_lshl_add_u64 v[40:41], v[40:41], 0, v[0:1]
	v_pk_mul_f32 v[18:19], v[18:19], v[38:39] op_sel_hi:[1,0]
	v_pk_mul_f32 v[20:21], v[20:21], v[38:39] op_sel_hi:[1,0]
	v_pk_mul_f32 v[2:3], v[2:3], v[38:39] op_sel_hi:[1,0]
	v_pk_mul_f32 v[4:5], v[4:5], v[38:39] op_sel_hi:[1,0]
	global_store_dwordx4 v[40:41], v[18:21], off
	global_store_dwordx4 v[40:41], v[2:5], off offset:128
	s_nop 0
	v_pk_mul_f32 v[18:19], v[22:23], v[38:39] op_sel_hi:[1,0]
	v_pk_mul_f32 v[20:21], v[24:25], v[38:39] op_sel_hi:[1,0]
	v_pk_mul_f32 v[2:3], v[6:7], v[38:39] op_sel_hi:[1,0]
	v_pk_mul_f32 v[4:5], v[8:9], v[38:39] op_sel_hi:[1,0]
	global_store_dwordx4 v[40:41], v[18:21], off offset:32
	global_store_dwordx4 v[40:41], v[2:5], off offset:160
	s_nop 0
	v_pk_mul_f32 v[18:19], v[26:27], v[38:39] op_sel_hi:[1,0]
	v_pk_mul_f32 v[20:21], v[28:29], v[38:39] op_sel_hi:[1,0]
	v_pk_mul_f32 v[2:3], v[10:11], v[38:39] op_sel_hi:[1,0]
	v_pk_mul_f32 v[4:5], v[12:13], v[38:39] op_sel_hi:[1,0]
	global_store_dwordx4 v[40:41], v[18:21], off offset:64
	global_store_dwordx4 v[40:41], v[2:5], off offset:192
	s_nop 0
	v_pk_mul_f32 v[18:19], v[30:31], v[38:39] op_sel_hi:[1,0]
	v_pk_mul_f32 v[20:21], v[32:33], v[38:39] op_sel_hi:[1,0]
	v_pk_mul_f32 v[2:3], v[14:15], v[38:39] op_sel_hi:[1,0]
	v_pk_mul_f32 v[4:5], v[16:17], v[38:39] op_sel_hi:[1,0]
	global_store_dwordx4 v[40:41], v[18:21], off offset:96
	global_store_dwordx4 v[40:41], v[2:5], off offset:224
	s_and_saveexec_b64 s[0:1], s[6:7]
	s_cbranch_execz .LBB0_302
	v_log_f32_e32 v0, v36
	v_lshlrev_b64 v[2:3], 5, v[34:35]
	v_lshl_add_u64 v[2:3], s[14:15], 0, v[2:3]
	s_lshl_b32 s90, s31, 2
	v_add_f32_e32 v0, v121, v0
	v_mul_f32_e32 v0, 0x3f317218, v0
	v_lshl_add_u64 v[2:3], v[2:3], 0, s[90:91]
	global_store_dword v[2:3], v0, off sc0 sc1
	s_branch .LBB0_302
